# GEMM K loop: one static s_setprio 1 for waves 4-7 over the whole loop replaces the 16 per-segment priority flips
# speedup vs baseline: 1.0079x; 1.0079x over previous
.LBB0_587:
	v_readlane_b32 s10, v255, 2
	v_mov_b64_e32 v[166:167], v[4:5]
	v_readlane_b32 s11, v255, 3
	v_mov_b64_e32 v[164:165], v[6:7]
	v_lshl_add_u64 v[130:131], v[0:1], 0, s[54:55]
	v_lshl_add_u64 v[170:171], s[10:11], 0, v[166:167]
	v_readlane_b32 s10, v255, 4
	v_readlane_b32 s11, v255, 5
	v_cndmask_b32_e64 v133, v0, v170, s[8:9]
	v_mov_b32_e32 v0, 0
	v_lshl_add_u64 v[168:169], s[10:11], 0, v[164:165]
	s_mov_b32 s92, s2
	s_mov_b32 s33, s22
	s_mov_b32 s15, s20
	s_mov_b32 s85, s21
	s_xor_b64 s[94:95], s[8:9], -1
	v_cndmask_b32_e64 v132, v1, v171, s[8:9]
	v_cndmask_b32_e64 v134, v3, v169, s[8:9]
	v_cndmask_b32_e64 v135, v2, v168, s[8:9]
	s_add_i32 s2, s12, -2
	v_lshl_add_u64 v[128:129], v[2:3], 0, s[52:53]
	s_mov_b32 s8, 0
	v_mov_b32_e32 v1, v0
	v_mov_b32_e32 v2, v0
	v_mov_b32_e32 v3, v0
	v_mov_b32_e32 v4, v0
	v_mov_b32_e32 v5, v0
	v_mov_b32_e32 v6, v0
	v_mov_b32_e32 v7, v0
	v_mov_b32_e32 v16, v0
	v_mov_b32_e32 v17, v0
	v_mov_b32_e32 v18, v0
	v_mov_b32_e32 v19, v0
	v_mov_b32_e32 v20, v0
	v_mov_b32_e32 v21, v0
	v_mov_b32_e32 v22, v0
	v_mov_b32_e32 v23, v0
	v_mov_b32_e32 v32, v0
	v_mov_b32_e32 v33, v0
	v_mov_b32_e32 v34, v0
	v_mov_b32_e32 v35, v0
	v_mov_b32_e32 v36, v0
	v_mov_b32_e32 v37, v0
	v_mov_b32_e32 v38, v0
	v_mov_b32_e32 v39, v0
	v_mov_b32_e32 v48, v0
	v_mov_b32_e32 v49, v0
	v_mov_b32_e32 v50, v0
	v_mov_b32_e32 v51, v0
	v_mov_b32_e32 v52, v0
	v_mov_b32_e32 v53, v0
	v_mov_b32_e32 v54, v0
	v_mov_b32_e32 v55, v0
	v_mov_b32_e32 v8, v0
	v_mov_b32_e32 v9, v0
	v_mov_b32_e32 v10, v0
	v_mov_b32_e32 v11, v0
	v_mov_b32_e32 v12, v0
	v_mov_b32_e32 v13, v0
	v_mov_b32_e32 v14, v0
	v_mov_b32_e32 v15, v0
	v_mov_b32_e32 v24, v0
	v_mov_b32_e32 v25, v0
	v_mov_b32_e32 v26, v0
	v_mov_b32_e32 v27, v0
	v_mov_b32_e32 v28, v0
	v_mov_b32_e32 v29, v0
	v_mov_b32_e32 v30, v0
	v_mov_b32_e32 v31, v0
	v_mov_b32_e32 v40, v0
	v_mov_b32_e32 v41, v0
	v_mov_b32_e32 v42, v0
	v_mov_b32_e32 v43, v0
	v_mov_b32_e32 v44, v0
	v_mov_b32_e32 v45, v0
	v_mov_b32_e32 v46, v0
	v_mov_b32_e32 v47, v0
	v_mov_b32_e32 v56, v0
	v_mov_b32_e32 v57, v0
	v_mov_b32_e32 v58, v0
	v_mov_b32_e32 v59, v0
	v_mov_b32_e32 v60, v0
	v_mov_b32_e32 v61, v0
	v_mov_b32_e32 v62, v0
	v_mov_b32_e32 v63, v0
	v_mov_b32_e32 v64, v0
	v_mov_b32_e32 v65, v0
	v_mov_b32_e32 v66, v0
	v_mov_b32_e32 v67, v0
	v_mov_b32_e32 v68, v0
	v_mov_b32_e32 v69, v0
	v_mov_b32_e32 v70, v0
	v_mov_b32_e32 v71, v0
	v_mov_b32_e32 v80, v0
	v_mov_b32_e32 v81, v0
	v_mov_b32_e32 v82, v0
	v_mov_b32_e32 v83, v0
	v_mov_b32_e32 v84, v0
	v_mov_b32_e32 v85, v0
	v_mov_b32_e32 v86, v0
	v_mov_b32_e32 v87, v0
	v_mov_b32_e32 v96, v0
	v_mov_b32_e32 v97, v0
	v_mov_b32_e32 v98, v0
	v_mov_b32_e32 v99, v0
	v_mov_b32_e32 v100, v0
	v_mov_b32_e32 v101, v0
	v_mov_b32_e32 v102, v0
	v_mov_b32_e32 v103, v0
	v_mov_b32_e32 v112, v0
	v_mov_b32_e32 v113, v0
	v_mov_b32_e32 v114, v0
	v_mov_b32_e32 v115, v0
	v_mov_b32_e32 v116, v0
	v_mov_b32_e32 v117, v0
	v_mov_b32_e32 v118, v0
	v_mov_b32_e32 v119, v0
	v_mov_b32_e32 v72, v0
	v_mov_b32_e32 v73, v0
	v_mov_b32_e32 v74, v0
	v_mov_b32_e32 v75, v0
	v_mov_b32_e32 v76, v0
	v_mov_b32_e32 v77, v0
	v_mov_b32_e32 v78, v0
	v_mov_b32_e32 v79, v0
	v_mov_b32_e32 v88, v0
	v_mov_b32_e32 v89, v0
	v_mov_b32_e32 v90, v0
	v_mov_b32_e32 v91, v0
	v_mov_b32_e32 v92, v0
	v_mov_b32_e32 v93, v0
	v_mov_b32_e32 v94, v0
	v_mov_b32_e32 v95, v0
	v_mov_b32_e32 v104, v0
	v_mov_b32_e32 v105, v0
	v_mov_b32_e32 v106, v0
	v_mov_b32_e32 v107, v0
	v_mov_b32_e32 v108, v0
	v_mov_b32_e32 v109, v0
	v_mov_b32_e32 v110, v0
	v_mov_b32_e32 v111, v0
	v_mov_b32_e32 v120, v0
	v_mov_b32_e32 v121, v0
	v_mov_b32_e32 v122, v0
	v_mov_b32_e32 v123, v0
	v_mov_b32_e32 v124, v0
	v_mov_b32_e32 v125, v0
	v_mov_b32_e32 v126, v0
	v_mov_b32_e32 v127, v0
	v_readfirstlane_b32 s98, v206
	s_nop 3
	s_cmpk_ge_u32 s98, 0x100
	s_cbranch_scc0 .Lprio_lo
	s_setprio 1
.Lprio_lo:
.LBB0_588:
	s_add_i32 s10, 0, 0x10000
	v_add_u32_e32 v148, s10, v184
	s_waitcnt lgkmcnt(0)
	ds_read_b128 v[136:139], v148
	ds_read_b128 v[140:143], v148 offset:1024
	ds_read_b128 v[144:147], v148 offset:2048
	ds_read_b128 v[148:151], v148 offset:3072
	s_add_i32 s9, s8, 2
	s_cmp_eq_u32 s2, s8
	v_lshl_add_u64 v[154:155], v[130:131], 0, s[54:55]
	s_cselect_b64 vcc, -1, 0
	v_cndmask_b32_e32 v155, v155, v132, vcc
	v_cndmask_b32_e32 v154, v154, v133, vcc
	v_cndmask_b32_e32 v211, v129, v134, vcc
	v_cndmask_b32_e32 v210, v128, v135, vcc
	v_lshl_add_u64 v[214:215], v[130:131], 0, v[162:163]
	s_add_i32 m0, s28, 0xc000
	ds_read_b128 v[172:175], v185
	ds_read_b128 v[176:179], v185 offset:1024
	ds_read_b128 v[180:183], v185 offset:2048
	ds_read_b128 v[186:189], v185 offset:3072
	ds_read_b128 v[190:193], v185 offset:4096
	ds_read_b128 v[194:197], v185 offset:5120
	ds_read_b128 v[198:201], v185 offset:6144
	ds_read_b128 v[202:205], v185 offset:7168
	global_load_lds_dwordx4 v[214:215], off
	v_lshl_add_u64 v[214:215], v[130:131], 0, v[160:161]
	s_add_i32 m0, s28, 0xe000
	s_nop 0
	global_load_lds_dwordx4 v[214:215], off
	s_waitcnt lgkmcnt(8)
	s_barrier
	s_waitcnt lgkmcnt(0)
	s_waitcnt lgkmcnt(0)
	v_mfma_f32_16x16x32_bf16 v[124:127], v[136:139], v[172:175], v[124:127]
	v_mfma_f32_16x16x32_bf16 v[120:123], v[144:147], v[172:175], v[120:123]
	v_mfma_f32_16x16x32_bf16 v[108:111], v[136:139], v[180:183], v[108:111]
	v_mfma_f32_16x16x32_bf16 v[104:107], v[144:147], v[180:183], v[104:107]
	v_mfma_f32_16x16x32_bf16 v[92:95], v[136:139], v[190:193], v[92:95]
	v_mfma_f32_16x16x32_bf16 v[88:91], v[144:147], v[190:193], v[88:91]
	v_mfma_f32_16x16x32_bf16 v[76:79], v[136:139], v[198:201], v[76:79]
	v_mfma_f32_16x16x32_bf16 v[72:75], v[144:147], v[198:201], v[72:75]
	v_mfma_f32_16x16x32_bf16 v[124:127], v[140:143], v[176:179], v[124:127]
	v_mfma_f32_16x16x32_bf16 v[120:123], v[148:151], v[176:179], v[120:123]
	v_mfma_f32_16x16x32_bf16 v[108:111], v[140:143], v[186:189], v[108:111]
	v_mfma_f32_16x16x32_bf16 v[104:107], v[148:151], v[186:189], v[104:107]
	v_mfma_f32_16x16x32_bf16 v[92:95], v[140:143], v[194:197], v[92:95]
	v_mfma_f32_16x16x32_bf16 v[88:91], v[148:151], v[194:197], v[88:91]
	v_mfma_f32_16x16x32_bf16 v[76:79], v[140:143], v[202:205], v[76:79]
	v_mfma_f32_16x16x32_bf16 v[72:75], v[148:151], v[202:205], v[72:75]
	s_barrier
	s_add_i32 s8, 0, 0x14000
	s_add_i32 s10, s10, s71
	v_add_u32_e32 v152, s8, v184
	v_lshl_add_u64 v[214:215], v[210:211], 0, v[156:157]
	s_mov_b32 m0, s10
	ds_read_b128 v[226:229], v152
	ds_read_b128 v[230:233], v152 offset:1024
	ds_read_b128 v[234:237], v152 offset:2048
	ds_read_b128 v[238:241], v152 offset:3072
	global_load_lds_dwordx4 v[214:215], off
	v_lshl_add_u64 v[216:217], v[210:211], 0, v[158:159]
	s_add_i32 m0, s10, 0x2000
	s_nop 0
	global_load_lds_dwordx4 v[216:217], off
	s_barrier
	s_waitcnt lgkmcnt(0)
	s_waitcnt lgkmcnt(0)
	v_mfma_f32_16x16x32_bf16 v[116:119], v[226:229], v[172:175], v[116:119]
	v_mfma_f32_16x16x32_bf16 v[112:115], v[234:237], v[172:175], v[112:115]
	v_mfma_f32_16x16x32_bf16 v[100:103], v[226:229], v[180:183], v[100:103]
	v_mfma_f32_16x16x32_bf16 v[96:99], v[234:237], v[180:183], v[96:99]
	v_mfma_f32_16x16x32_bf16 v[84:87], v[226:229], v[190:193], v[84:87]
	v_mfma_f32_16x16x32_bf16 v[80:83], v[234:237], v[190:193], v[80:83]
	v_mfma_f32_16x16x32_bf16 v[68:71], v[226:229], v[198:201], v[68:71]
	v_mfma_f32_16x16x32_bf16 v[64:67], v[234:237], v[198:201], v[64:67]
	v_mfma_f32_16x16x32_bf16 v[116:119], v[230:233], v[176:179], v[116:119]
	v_mfma_f32_16x16x32_bf16 v[112:115], v[238:241], v[176:179], v[112:115]
	v_mfma_f32_16x16x32_bf16 v[100:103], v[230:233], v[186:189], v[100:103]
	v_mfma_f32_16x16x32_bf16 v[96:99], v[238:241], v[186:189], v[96:99]
	v_mfma_f32_16x16x32_bf16 v[84:87], v[230:233], v[194:197], v[84:87]
	v_mfma_f32_16x16x32_bf16 v[80:83], v[238:241], v[194:197], v[80:83]
	v_mfma_f32_16x16x32_bf16 v[68:71], v[230:233], v[202:205], v[68:71]
	v_mfma_f32_16x16x32_bf16 v[64:67], v[238:241], v[202:205], v[64:67]
	s_mov_b32 m0, s28
	v_lshl_add_u64 v[218:219], v[154:155], 0, v[156:157]
	s_barrier
	ds_read_b128 v[172:175], v185 offset:16384
	ds_read_b128 v[176:179], v185 offset:17408
	ds_read_b128 v[180:183], v185 offset:18432
	ds_read_b128 v[186:189], v185 offset:19456
	ds_read_b128 v[190:193], v185 offset:20480
	ds_read_b128 v[194:197], v185 offset:21504
	ds_read_b128 v[198:201], v185 offset:22528
	ds_read_b128 v[202:205], v185 offset:23552
	global_load_lds_dwordx4 v[218:219], off
	v_lshl_add_u64 v[220:221], v[154:155], 0, v[158:159]
	s_mov_b32 m0, s29
	s_nop 0
	global_load_lds_dwordx4 v[220:221], off
	s_barrier
	s_waitcnt lgkmcnt(0)
	s_waitcnt lgkmcnt(0)
	v_mfma_f32_16x16x32_bf16 v[60:63], v[136:139], v[172:175], v[60:63]
	v_mfma_f32_16x16x32_bf16 v[56:59], v[144:147], v[172:175], v[56:59]
	v_mfma_f32_16x16x32_bf16 v[44:47], v[136:139], v[180:183], v[44:47]
	v_mfma_f32_16x16x32_bf16 v[40:43], v[144:147], v[180:183], v[40:43]
	v_mfma_f32_16x16x32_bf16 v[28:31], v[136:139], v[190:193], v[28:31]
	v_mfma_f32_16x16x32_bf16 v[24:27], v[144:147], v[190:193], v[24:27]
	v_mfma_f32_16x16x32_bf16 v[12:15], v[136:139], v[198:201], v[12:15]
	v_mfma_f32_16x16x32_bf16 v[8:11], v[144:147], v[198:201], v[8:11]
	v_mfma_f32_16x16x32_bf16 v[60:63], v[140:143], v[176:179], v[60:63]
	v_mfma_f32_16x16x32_bf16 v[56:59], v[148:151], v[176:179], v[56:59]
	v_mfma_f32_16x16x32_bf16 v[44:47], v[140:143], v[186:189], v[44:47]
	v_mfma_f32_16x16x32_bf16 v[40:43], v[148:151], v[186:189], v[40:43]
	v_mfma_f32_16x16x32_bf16 v[28:31], v[140:143], v[194:197], v[28:31]
	v_mfma_f32_16x16x32_bf16 v[24:27], v[148:151], v[194:197], v[24:27]
	v_mfma_f32_16x16x32_bf16 v[12:15], v[140:143], v[202:205], v[12:15]
	v_mfma_f32_16x16x32_bf16 v[8:11], v[148:151], v[202:205], v[8:11]
	s_barrier
	v_lshl_add_u64 v[136:137], v[210:211], 0, s[16:17]
	s_add_i32 s8, s8, s71
	v_lshl_add_u64 v[210:211], v[136:137], 0, v[156:157]
	s_mov_b32 m0, s8
	v_lshl_add_u64 v[224:225], v[136:137], 0, v[158:159]
	global_load_lds_dwordx4 v[210:211], off
	s_add_i32 m0, s8, 0x2000
	s_nop 0
	global_load_lds_dwordx4 v[224:225], off
	s_waitcnt vmcnt(6)
	s_barrier
	v_mfma_f32_16x16x32_bf16 v[52:55], v[226:229], v[172:175], v[52:55]
	v_mfma_f32_16x16x32_bf16 v[48:51], v[234:237], v[172:175], v[48:51]
	v_mfma_f32_16x16x32_bf16 v[36:39], v[226:229], v[180:183], v[36:39]
	v_mfma_f32_16x16x32_bf16 v[32:35], v[234:237], v[180:183], v[32:35]
	v_mfma_f32_16x16x32_bf16 v[20:23], v[226:229], v[190:193], v[20:23]
	v_mfma_f32_16x16x32_bf16 v[16:19], v[234:237], v[190:193], v[16:19]
	v_mfma_f32_16x16x32_bf16 v[4:7], v[226:229], v[198:201], v[4:7]
	v_mfma_f32_16x16x32_bf16 v[0:3], v[234:237], v[198:201], v[0:3]
	v_mfma_f32_16x16x32_bf16 v[52:55], v[230:233], v[176:179], v[52:55]
	v_mfma_f32_16x16x32_bf16 v[48:51], v[238:241], v[176:179], v[48:51]
	v_mfma_f32_16x16x32_bf16 v[36:39], v[230:233], v[186:189], v[36:39]
	v_mfma_f32_16x16x32_bf16 v[32:35], v[238:241], v[186:189], v[32:35]
	v_mfma_f32_16x16x32_bf16 v[20:23], v[230:233], v[194:197], v[20:23]
	v_mfma_f32_16x16x32_bf16 v[16:19], v[238:241], v[194:197], v[16:19]
	v_mfma_f32_16x16x32_bf16 v[4:7], v[230:233], v[202:205], v[4:7]
	v_mfma_f32_16x16x32_bf16 v[0:3], v[238:241], v[202:205], v[0:3]
	s_add_i32 s8, 0, 0x18000
	v_add_u32_e32 v148, s8, v184
	s_barrier
	ds_read_b128 v[136:139], v148
	ds_read_b128 v[140:143], v148 offset:1024
	ds_read_b128 v[144:147], v148 offset:2048
	ds_read_b128 v[148:151], v148 offset:3072
	v_lshl_add_u64 v[154:155], v[154:155], 0, s[16:17]
	s_mov_b32 m0, s35
	v_lshl_add_u64 v[226:227], v[154:155], 0, v[156:157]
	ds_read_b128 v[172:175], v185 offset:32768
	ds_read_b128 v[176:179], v185 offset:33792
	ds_read_b128 v[180:183], v185 offset:34816
	ds_read_b128 v[186:189], v185 offset:35840
	ds_read_b128 v[190:193], v185 offset:36864
	ds_read_b128 v[194:197], v185 offset:37888
	ds_read_b128 v[198:201], v185 offset:38912
	ds_read_b128 v[202:205], v185 offset:39936
	global_load_lds_dwordx4 v[226:227], off
	v_lshl_add_u64 v[154:155], v[154:155], 0, v[158:159]
	s_mov_b32 m0, s74
	s_nop 0
	global_load_lds_dwordx4 v[154:155], off
	s_waitcnt lgkmcnt(8)
	s_barrier
	s_waitcnt lgkmcnt(0)
	s_waitcnt lgkmcnt(0)
	v_mfma_f32_16x16x32_bf16 v[124:127], v[136:139], v[172:175], v[124:127]
	v_mfma_f32_16x16x32_bf16 v[120:123], v[144:147], v[172:175], v[120:123]
	v_mfma_f32_16x16x32_bf16 v[108:111], v[136:139], v[180:183], v[108:111]
	v_mfma_f32_16x16x32_bf16 v[104:107], v[144:147], v[180:183], v[104:107]
	v_mfma_f32_16x16x32_bf16 v[92:95], v[136:139], v[190:193], v[92:95]
	v_mfma_f32_16x16x32_bf16 v[88:91], v[144:147], v[190:193], v[88:91]
	v_mfma_f32_16x16x32_bf16 v[76:79], v[136:139], v[198:201], v[76:79]
	v_mfma_f32_16x16x32_bf16 v[72:75], v[144:147], v[198:201], v[72:75]
	v_mfma_f32_16x16x32_bf16 v[124:127], v[140:143], v[176:179], v[124:127]
	v_mfma_f32_16x16x32_bf16 v[120:123], v[148:151], v[176:179], v[120:123]
	v_mfma_f32_16x16x32_bf16 v[108:111], v[140:143], v[186:189], v[108:111]
	v_mfma_f32_16x16x32_bf16 v[104:107], v[148:151], v[186:189], v[104:107]
	v_mfma_f32_16x16x32_bf16 v[92:95], v[140:143], v[194:197], v[92:95]
	v_mfma_f32_16x16x32_bf16 v[88:91], v[148:151], v[194:197], v[88:91]
	v_mfma_f32_16x16x32_bf16 v[76:79], v[140:143], v[202:205], v[76:79]
	v_mfma_f32_16x16x32_bf16 v[72:75], v[148:151], v[202:205], v[72:75]
	s_barrier
	s_add_i32 s10, 0, 0x1c000
	s_add_i32 s8, s8, s71
	v_add_u32_e32 v152, s10, v184
	v_lshl_add_u64 v[154:155], v[214:215], 0, s[54:55]
	s_mov_b32 m0, s8
	ds_read_b128 v[226:229], v152
	ds_read_b128 v[230:233], v152 offset:1024
	ds_read_b128 v[234:237], v152 offset:2048
	ds_read_b128 v[238:241], v152 offset:3072
	global_load_lds_dwordx4 v[154:155], off
	v_lshl_add_u64 v[154:155], v[216:217], 0, s[54:55]
	s_add_i32 m0, s8, 0x2000
	s_nop 0
	global_load_lds_dwordx4 v[154:155], off
	s_barrier
	s_waitcnt lgkmcnt(0)
	s_waitcnt lgkmcnt(0)
	v_mfma_f32_16x16x32_bf16 v[116:119], v[226:229], v[172:175], v[116:119]
	v_mfma_f32_16x16x32_bf16 v[112:115], v[234:237], v[172:175], v[112:115]
	v_mfma_f32_16x16x32_bf16 v[100:103], v[226:229], v[180:183], v[100:103]
	v_mfma_f32_16x16x32_bf16 v[96:99], v[234:237], v[180:183], v[96:99]
	v_mfma_f32_16x16x32_bf16 v[84:87], v[226:229], v[190:193], v[84:87]
	v_mfma_f32_16x16x32_bf16 v[80:83], v[234:237], v[190:193], v[80:83]
	v_mfma_f32_16x16x32_bf16 v[68:71], v[226:229], v[198:201], v[68:71]
	v_mfma_f32_16x16x32_bf16 v[64:67], v[234:237], v[198:201], v[64:67]
	v_mfma_f32_16x16x32_bf16 v[116:119], v[230:233], v[176:179], v[116:119]
	v_mfma_f32_16x16x32_bf16 v[112:115], v[238:241], v[176:179], v[112:115]
	v_mfma_f32_16x16x32_bf16 v[100:103], v[230:233], v[186:189], v[100:103]
	v_mfma_f32_16x16x32_bf16 v[96:99], v[238:241], v[186:189], v[96:99]
	v_mfma_f32_16x16x32_bf16 v[84:87], v[230:233], v[194:197], v[84:87]
	v_mfma_f32_16x16x32_bf16 v[80:83], v[238:241], v[194:197], v[80:83]
	v_mfma_f32_16x16x32_bf16 v[68:71], v[230:233], v[202:205], v[68:71]
	v_mfma_f32_16x16x32_bf16 v[64:67], v[238:241], v[202:205], v[64:67]
	s_mov_b32 m0, s4
	v_lshl_add_u64 v[154:155], v[218:219], 0, s[54:55]
	s_barrier
	ds_read_b128 v[172:175], v185 offset:49152
	ds_read_b128 v[176:179], v185 offset:50176
	ds_read_b128 v[180:183], v185 offset:51200
	ds_read_b128 v[186:189], v185 offset:52224
	ds_read_b128 v[190:193], v185 offset:53248
	ds_read_b128 v[194:197], v185 offset:54272
	ds_read_b128 v[198:201], v185 offset:55296
	ds_read_b128 v[202:205], v185 offset:56320
	global_load_lds_dwordx4 v[154:155], off
	v_lshl_add_u64 v[154:155], v[220:221], 0, s[54:55]
	s_mov_b32 m0, s5
	s_nop 0
	global_load_lds_dwordx4 v[154:155], off
	s_barrier
	s_waitcnt lgkmcnt(0)
	s_waitcnt lgkmcnt(0)
	v_mfma_f32_16x16x32_bf16 v[60:63], v[136:139], v[172:175], v[60:63]
	v_mfma_f32_16x16x32_bf16 v[56:59], v[144:147], v[172:175], v[56:59]
	v_mfma_f32_16x16x32_bf16 v[44:47], v[136:139], v[180:183], v[44:47]
	v_mfma_f32_16x16x32_bf16 v[40:43], v[144:147], v[180:183], v[40:43]
	v_mfma_f32_16x16x32_bf16 v[28:31], v[136:139], v[190:193], v[28:31]
	v_mfma_f32_16x16x32_bf16 v[24:27], v[144:147], v[190:193], v[24:27]
	v_mfma_f32_16x16x32_bf16 v[12:15], v[136:139], v[198:201], v[12:15]
	v_mfma_f32_16x16x32_bf16 v[8:11], v[144:147], v[198:201], v[8:11]
	v_mfma_f32_16x16x32_bf16 v[60:63], v[140:143], v[176:179], v[60:63]
	v_mfma_f32_16x16x32_bf16 v[56:59], v[148:151], v[176:179], v[56:59]
	v_mfma_f32_16x16x32_bf16 v[44:47], v[140:143], v[186:189], v[44:47]
	v_mfma_f32_16x16x32_bf16 v[40:43], v[148:151], v[186:189], v[40:43]
	v_mfma_f32_16x16x32_bf16 v[28:31], v[140:143], v[194:197], v[28:31]
	v_mfma_f32_16x16x32_bf16 v[24:27], v[148:151], v[194:197], v[24:27]
	v_mfma_f32_16x16x32_bf16 v[12:15], v[140:143], v[202:205], v[12:15]
	v_mfma_f32_16x16x32_bf16 v[8:11], v[148:151], v[202:205], v[8:11]
	s_barrier
	s_add_i32 s8, s10, s71
	v_lshl_add_u64 v[136:137], v[210:211], 0, s[54:55]
	s_mov_b32 m0, s8
	s_nop 0
	global_load_lds_dwordx4 v[136:137], off
	v_lshl_add_u64 v[136:137], v[224:225], 0, s[54:55]
	s_add_i32 m0, s8, 0x2000
	s_nop 0
	global_load_lds_dwordx4 v[136:137], off
	s_waitcnt vmcnt(6)
	s_barrier
	v_mfma_f32_16x16x32_bf16 v[52:55], v[226:229], v[172:175], v[52:55]
	v_mfma_f32_16x16x32_bf16 v[48:51], v[234:237], v[172:175], v[48:51]
	v_mfma_f32_16x16x32_bf16 v[36:39], v[226:229], v[180:183], v[36:39]
	v_mfma_f32_16x16x32_bf16 v[32:35], v[234:237], v[180:183], v[32:35]
	v_mfma_f32_16x16x32_bf16 v[20:23], v[226:229], v[190:193], v[20:23]
	v_mfma_f32_16x16x32_bf16 v[16:19], v[234:237], v[190:193], v[16:19]
	v_mfma_f32_16x16x32_bf16 v[4:7], v[226:229], v[198:201], v[4:7]
	v_mfma_f32_16x16x32_bf16 v[0:3], v[234:237], v[198:201], v[0:3]
	v_mfma_f32_16x16x32_bf16 v[52:55], v[230:233], v[176:179], v[52:55]
	v_mfma_f32_16x16x32_bf16 v[48:51], v[238:241], v[176:179], v[48:51]
	v_mfma_f32_16x16x32_bf16 v[36:39], v[230:233], v[186:189], v[36:39]
	v_mfma_f32_16x16x32_bf16 v[32:35], v[238:241], v[186:189], v[32:35]
	v_mfma_f32_16x16x32_bf16 v[20:23], v[230:233], v[194:197], v[20:23]
	v_mfma_f32_16x16x32_bf16 v[16:19], v[238:241], v[194:197], v[16:19]
	v_mfma_f32_16x16x32_bf16 v[4:7], v[230:233], v[202:205], v[4:7]
	v_mfma_f32_16x16x32_bf16 v[0:3], v[238:241], v[202:205], v[0:3]
	v_lshl_add_u64 v[128:129], v[128:129], 0, s[52:53]
	v_lshl_add_u64 v[130:131], v[130:131], 0, s[52:53]
	s_cmp_ge_i32 s9, s12
	s_mov_b32 s8, s9
	s_barrier
	s_cbranch_scc0 .LBB0_588
	s_setprio 0
	v_mov_b32_e32 v191, v206
	s_lshl_b32 s40, s27, 8
	v_readfirstlane_b32 s2, v191
	s_ashr_i32 s26, s2, 2
	s_bfe_u32 s89, s2, 0x20006
	v_bfe_u32 v188, v191, 4, 2
	s_andn2_b32 s26, s26, 63
	v_and_b32_e32 v189, 15, v191
	s_add_i32 s86, s26, s40
	s_lshl_b32 s41, s89, 5
	v_lshlrev_b32_e32 v190, 2, v188
	v_or_b32_e32 v172, s86, v189
	v_or_b32_e32 v187, s41, v190
	v_lshl_or_b32 v186, v188, 3, s41
	s_cmp_lt_i32 s93, 3
	s_mov_b64 s[8:9], -1
	s_cbranch_scc1 .LBB0_1004
	s_cmp_lt_i32 s93, 4
	s_cbranch_scc1 .LBB0_906
	s_cmp_lt_i32 s93, 6
	s_cbranch_scc1 .LBB0_731
	s_cmp_lt_i32 s93, 9
	s_cbranch_scc0 .LBB0_730
	s_cmp_eq_u32 s93, 7
	s_movk_i32 s2, 0x800
	s_cselect_b32 s2, 0x400, s2
	s_cmp_lg_u32 s93, 6
	s_cselect_b32 s2, s2, 0
	v_lshl_or_b32 v174, s14, 8, v186
	v_mov_b64_e32 v[128:129], s[44:45]
	s_movk_i32 s8, 0x1800
	v_mad_i64_i32 v[128:129], s[8:9], v172, s8, v[128:129]
	s_lshl_b32 s2, s2, 1
	v_ashrrev_i32_e32 v175, 31, v174
	v_lshl_add_u64 v[128:129], v[128:129], 0, s[2:3]
	v_lshlrev_b64 v[176:177], 1, v[174:175]
	v_lshl_add_u64 v[128:129], v[128:129], 0, v[176:177]
	v_mov_b64_e32 v[214:215], v[128:129]
	flat_load_dwordx4 v[140:143], v[128:129]
	v_ashrrev_i32_e32 v173, 31, v172
	v_readlane_b32 s8, v254, 43
	v_lshlrev_b64 v[178:179], 11, v[172:173]
	v_readlane_b32 s9, v254, 44
	s_cmp_eq_u32 s93, 8
	s_cselect_b64 s[10:11], -1, 0
	v_lshl_add_u64 v[130:131], s[8:9], 0, v[178:179]
	s_cmp_lg_u32 s93, 8
	v_lshl_add_u64 v[144:145], v[130:131], 0, v[176:177]
	v_mov_b64_e32 v[216:217], v[144:145]
	s_cbranch_scc1 .LBB0_595
	flat_load_dwordx4 v[132:135], v[144:145]
